# k13 + FoX flash loop: forget-gate cumsum row staged in the wave's LDS once per unit, per-tile ds_read instead of exposed global loads
# speedup vs baseline: 1.0035x; 1.0035x over previous
.LBB0_1548:
	s_cmp_gt_u32 s18, s25
	s_cbranch_scc1 .LBB0_1562
	v_readlane_b32 s2, v255, 16
	s_add_u32 s2, s2, s4
	v_readlane_b32 s3, v255, 17
	s_addc_u32 s3, s3, s5
	s_lshl_b64 s[4:5], s[36:37], 13
	v_readlane_b32 s8, v255, 20
	v_ashrrev_i32_e32 v0, 3, v188
	s_add_u32 s4, s8, s4
	v_readlane_b32 s8, v255, 21
	v_lshlrev_b32_e32 v14, 3, v188
	v_and_b32_e32 v150, -4, v0
	s_addc_u32 s5, s8, s5
	v_ashrrev_i32_e32 v15, 31, v14
	v_ashrrev_i32_e32 v151, 31, v150
	v_lshlrev_b64 v[16:17], 1, v[14:15]
	v_lshl_add_u64 v[154:155], v[150:151], 2, s[4:5]
	v_mov_b32_e32 v151, 0
	v_lshl_add_u64 v[14:15], s[2:3], 0, v[16:17]
	v_lshl_add_u64 v[152:153], s[0:1], 0, v[16:17]
	v_subrev_u32_e32 v149, 32, v190
	v_mov_b32_e32 v191, 0xff800000
	v_mov_b32_e32 v16, 0
	v_mov_b32_e32 v17, v151
	v_mov_b32_e32 v18, 0
	v_mov_b32_e32 v19, v151
	v_mov_b32_e32 v20, 0
	v_mov_b32_e32 v21, v151
	v_mov_b32_e32 v22, 0
	v_mov_b32_e32 v23, v151
	v_mov_b32_e32 v24, 0
	v_mov_b32_e32 v25, v151
	v_mov_b32_e32 v26, 0
	v_mov_b32_e32 v27, v151
	v_mov_b32_e32 v28, 0
	v_mov_b32_e32 v29, v151
	v_mov_b32_e32 v30, 0
	v_mov_b32_e32 v31, v151
	v_mov_b32_e32 v64, 0
	v_mov_b32_e32 v65, v151
	v_mov_b32_e32 v66, 0
	v_mov_b32_e32 v67, v151
	v_mov_b32_e32 v68, 0
	v_mov_b32_e32 v69, v151
	v_mov_b32_e32 v70, 0
	v_mov_b32_e32 v71, v151
	v_mov_b32_e32 v72, 0
	v_mov_b32_e32 v73, v151
	v_mov_b32_e32 v74, 0
	v_mov_b32_e32 v75, v151
	v_mov_b32_e32 v76, 0
	v_mov_b32_e32 v77, v151
	v_mov_b32_e32 v78, 0
	v_mov_b32_e32 v79, v151
	v_lshlrev_b32_e32 v184, 4, v188
	v_add_u32_e32 v185, 0x1000, v184
	global_load_dwordx4 v[32:35], v184, s[4:5]
	global_load_dwordx4 v[36:39], v184, s[4:5] offset:1024
	global_load_dwordx4 v[40:43], v184, s[4:5] offset:2048
	global_load_dwordx4 v[44:47], v184, s[4:5] offset:3072
	global_load_dwordx4 v[48:51], v185, s[4:5]
	global_load_dwordx4 v[52:55], v185, s[4:5] offset:1024
	global_load_dwordx4 v[56:59], v185, s[4:5] offset:2048
	global_load_dwordx4 v[60:63], v185, s[4:5] offset:3072
	v_readlane_b32 s2, v253, 16
	s_lshl_b32 s2, s2, 14
	s_nop 1
	v_add_u32_e32 v0, s2, v184
	v_lshl_add_u32 v198, v150, 2, s2
	s_waitcnt vmcnt(0)
	ds_write_b128 v0, v[32:35]
	ds_write_b128 v0, v[36:39] offset:1024
	ds_write_b128 v0, v[40:43] offset:2048
	ds_write_b128 v0, v[44:47] offset:3072
	ds_write_b128 v0, v[48:51] offset:4096
	ds_write_b128 v0, v[52:55] offset:5120
	ds_write_b128 v0, v[56:59] offset:6144
	ds_write_b128 v0, v[60:63] offset:7168
	s_waitcnt lgkmcnt(0)
	s_mov_b32 s0, s18

.LBB0_1554:
	s_lshl_b32 s4, s18, 6
	s_ashr_i32 s5, s4, 31
	s_lshl_b32 s2, s18, 8
	v_add_u32_e32 v184, s2, v198
	ds_read_b128 v[32:35], v184
	ds_read_b128 v[36:39], v184 offset:32
	ds_read_b128 v[40:43], v184 offset:64
	ds_read_b128 v[44:47], v184 offset:96
	ds_read_b128 v[48:51], v184 offset:128
	ds_read_b128 v[52:55], v184 offset:160
	ds_read_b128 v[56:59], v184 offset:192
	ds_read_b128 v[60:63], v184 offset:224
	s_ashr_i32 s19, s18, 31
	s_lshl_b64 s[2:3], s[18:19], 13
	v_lshl_add_u64 v[184:185], v[14:15], 0, s[2:3]
	global_load_dwordx4 v[144:147], v[184:185], off
	global_load_dwordx4 v[140:143], v[184:185], off offset:1024
	global_load_dwordx4 v[136:139], v[184:185], off offset:2048
	global_load_dwordx4 v[132:135], v[184:185], off offset:3072
	v_add_co_u32_e32 v184, vcc, 0x1000, v184
	s_waitcnt vmcnt(11) lgkmcnt(0)
	v_mfma_f32_32x32x16_bf16 v[32:47], v[84:87], v[2:5], v[32:47]
	v_addc_co_u32_e32 v185, vcc, 0, v185, vcc
	global_load_dwordx4 v[128:131], v[184:185], off
	global_load_dwordx4 v[124:127], v[184:185], off offset:1024
	global_load_dwordx4 v[120:123], v[184:185], off offset:2048
	global_load_dwordx4 v[116:119], v[184:185], off offset:3072
	s_andn2_b64 vcc, exec, s[8:9]
	s_waitcnt vmcnt(11)
	v_mfma_f32_32x32x16_bf16 v[48:63], v[100:103], v[2:5], v[48:63]
	v_mfma_f32_32x32x16_bf16 v[32:47], v[88:91], v[6:9], v[32:47]
	s_waitcnt vmcnt(10)
	v_mfma_f32_32x32x16_bf16 v[48:63], v[104:107], v[6:9], v[48:63]
	v_mfma_f32_32x32x16_bf16 v[32:47], v[92:95], v[10:13], v[32:47]
	s_waitcnt vmcnt(9)
	v_mfma_f32_32x32x16_bf16 v[48:63], v[108:111], v[10:13], v[48:63]
	v_mfma_f32_32x32x16_bf16 v[32:47], v[96:99], v[80:83], v[32:47]
	s_waitcnt vmcnt(8)
	v_mfma_f32_32x32x16_bf16 v[48:63], v[112:115], v[80:83], v[48:63]
	s_cbranch_vccnz .Lattn_nonext_1550
	s_ashr_i32 s1, s0, 31
	s_lshl_b64 s[2:3], s[0:1], 13
	v_lshl_add_u64 v[184:185], v[152:153], 0, s[2:3]
	global_load_dwordx4 v[84:87], v[184:185], off
	global_load_dwordx4 v[88:91], v[184:185], off offset:1024
	global_load_dwordx4 v[92:95], v[184:185], off offset:2048
	global_load_dwordx4 v[96:99], v[184:185], off offset:3072
	v_add_co_u32_e32 v184, vcc, 0x1000, v184
	s_nop 1
	v_addc_co_u32_e32 v185, vcc, 0, v185, vcc
	global_load_dwordx4 v[100:103], v[184:185], off
	global_load_dwordx4 v[104:107], v[184:185], off offset:1024
	global_load_dwordx4 v[108:111], v[184:185], off offset:2048
	global_load_dwordx4 v[112:115], v[184:185], off offset:3072
